# modulate phases: gain/scale/shift loads of column chunks 1..3 issued with chunk 0 (counted vmcnt) instead of one load latency + store drain per chunk
# baseline (speedup 1.0000x reference)
.LBB0_92:
	s_waitcnt vmcnt(0)
	v_pk_mul_f32 v[66:67], v[30:31], v[30:31]
	v_pk_mul_f32 v[76:77], v[26:27], v[26:27]
	s_waitcnt vmcnt(2)
	v_mov_b32_e32 v124, v10
	v_mov_b32_e32 v125, v14
	v_pk_mul_f32 v[70:71], v[32:33], v[32:33]
	v_pk_mul_f32 v[78:79], v[28:29], v[28:29]
	v_pk_mul_f32 v[124:125], v[124:125], v[124:125]
	v_mov_b32_e32 v126, v11
	v_mov_b32_e32 v127, v15
	v_add_f32_e32 v66, v67, v66
	v_add_f32_e32 v67, v77, v76
	v_pk_fma_f32 v[124:125], v[126:127], v[126:127], v[124:125]
	v_mov_b32_e32 v126, v12
	v_mov_b32_e32 v127, v16
	v_add_f32_e32 v66, v70, v66
	v_add_f32_e32 v67, v78, v67
	v_pk_mul_f32 v[84:85], v[22:23], v[22:23]
	v_pk_fma_f32 v[124:125], v[126:127], v[126:127], v[124:125]
	v_mov_b32_e32 v126, v13
	v_mov_b32_e32 v127, v17
	v_add_f32_e32 v66, v71, v66
	v_add_f32_e32 v67, v79, v67
	v_pk_mul_f32 v[86:87], v[24:25], v[24:25]
	v_pk_fma_f32 v[124:125], v[126:127], v[126:127], v[124:125]
	v_mov_b32_e32 v126, v42
	v_mov_b32_e32 v127, v46
	v_add_f32_e32 v66, v67, v66
	v_add_f32_e32 v67, v85, v84
	v_pk_mul_f32 v[126:127], v[126:127], v[126:127]
	v_mov_b32_e32 v128, v43
	v_mov_b32_e32 v129, v47
	v_add_f32_e32 v67, v86, v67
	v_pk_mul_f32 v[116:117], v[18:19], v[18:19]
	v_pk_fma_f32 v[126:127], v[128:129], v[128:129], v[126:127]
	v_mov_b32_e32 v128, v44
	v_mov_b32_e32 v129, v48
	v_add_f32_e32 v67, v87, v67
	v_pk_mul_f32 v[118:119], v[20:21], v[20:21]
	v_pk_fma_f32 v[126:127], v[128:129], v[128:129], v[126:127]
	v_mov_b32_e32 v128, v45
	v_mov_b32_e32 v129, v49
	v_add_f32_e32 v66, v67, v66
	v_add_f32_e32 v67, v117, v116
	v_pk_fma_f32 v[126:127], v[128:129], v[128:129], v[126:127]
	s_waitcnt vmcnt(0)
	v_mov_b32_e32 v128, v2
	v_mov_b32_e32 v129, v6
	v_add_f32_e32 v67, v118, v67
	v_pk_mul_f32 v[128:129], v[128:129], v[128:129]
	v_mov_b32_e32 v130, v3
	v_mov_b32_e32 v131, v7
	v_add_f32_e32 v67, v119, v67
	v_pk_fma_f32 v[128:129], v[130:131], v[130:131], v[128:129]
	v_mov_b32_e32 v130, v4
	v_mov_b32_e32 v131, v8
	v_add_f32_e32 v66, v67, v66
	v_pk_fma_f32 v[128:129], v[130:131], v[130:131], v[128:129]
	v_mov_b32_e32 v130, v5
	v_mov_b32_e32 v131, v9
	v_add_f32_e32 v66, v125, v66
	v_pk_fma_f32 v[128:129], v[130:131], v[130:131], v[128:129]
	v_add_f32_e32 v66, v124, v66
	v_add_f32_e32 v66, v129, v66
	v_add_f32_e32 v69, v128, v66
	v_mov_b32_e32 v66, v34
	v_mov_b32_e32 v67, v38
	v_pk_mul_f32 v[66:67], v[66:67], v[66:67]
	v_mov_b32_e32 v70, v35
	v_mov_b32_e32 v71, v39
	v_pk_fma_f32 v[66:67], v[70:71], v[70:71], v[66:67]
	v_mov_b32_e32 v70, v36
	v_mov_b32_e32 v71, v40
	v_pk_mul_f32 v[72:73], v[62:63], v[62:63]
	v_pk_mul_f32 v[80:81], v[58:59], v[58:59]
	v_pk_fma_f32 v[66:67], v[70:71], v[70:71], v[66:67]
	v_mov_b32_e32 v70, v37
	v_mov_b32_e32 v71, v41
	v_pk_mul_f32 v[74:75], v[64:65], v[64:65]
	v_pk_mul_f32 v[82:83], v[60:61], v[60:61]
	v_pk_fma_f32 v[66:67], v[70:71], v[70:71], v[66:67]
	v_add_f32_e32 v70, v73, v72
	v_add_f32_e32 v71, v81, v80
	v_add_f32_e32 v70, v74, v70
	v_add_f32_e32 v71, v82, v71
	v_pk_mul_f32 v[88:89], v[54:55], v[54:55]
	v_add_f32_e32 v70, v75, v70
	v_add_f32_e32 v71, v83, v71
	v_pk_mul_f32 v[114:115], v[56:57], v[56:57]
	v_add_f32_e32 v70, v71, v70
	v_add_f32_e32 v71, v89, v88
	v_add_f32_e32 v71, v114, v71
	v_pk_mul_f32 v[120:121], v[50:51], v[50:51]
	v_add_f32_e32 v71, v115, v71
	v_pk_mul_f32 v[122:123], v[52:53], v[52:53]
	v_add_f32_e32 v70, v71, v70
	v_add_f32_e32 v71, v121, v120
	v_add_f32_e32 v71, v122, v71
	v_add_f32_e32 v71, v123, v71
	v_add_f32_e32 v70, v71, v70
	v_add_f32_e32 v70, v127, v70
	v_add_f32_e32 v70, v126, v70
	v_add_f32_e32 v67, v67, v70
	v_add_f32_e32 v66, v66, v67
	v_mov_b32_e32 v105, v1
	v_add_f32_dpp v67, v69, v69 quad_perm:[1,0,3,2] row_mask:0xf bank_mask:0xf bound_ctrl:1
	v_mov_b32_e32 v69, v1
	v_add_f32_dpp v66, v66, v66 quad_perm:[1,0,3,2] row_mask:0xf bank_mask:0xf bound_ctrl:1
	v_add_f32_dpp v67, v67, v67 quad_perm:[2,3,0,1] row_mask:0xf bank_mask:0xf bound_ctrl:1
	v_mov_b32_e32 v107, v1
	v_add_f32_dpp v66, v66, v66 quad_perm:[2,3,0,1] row_mask:0xf bank_mask:0xf bound_ctrl:1
	v_add_f32_dpp v67, v67, v67 row_half_mirror row_mask:0xf bank_mask:0xf bound_ctrl:1
	v_mov_b32_e32 v109, v1
	v_add_f32_dpp v66, v66, v66 row_half_mirror row_mask:0xf bank_mask:0xf bound_ctrl:1
	v_add_f32_dpp v67, v67, v67 row_mirror row_mask:0xf bank_mask:0xf bound_ctrl:1
	s_add_i32 s7, s7, s96
	v_add_f32_dpp v66, v66, v66 row_mirror row_mask:0xf bank_mask:0xf bound_ctrl:1
	v_mov_b32_dpp v69, v67 row_bcast:15 row_mask:0xa bank_mask:0xf
	v_add_f32_e32 v67, v67, v69
	v_mov_b32_e32 v69, v1
	s_cmpk_gt_i32 s7, 0x2ff
	s_nop 0
	v_mov_b32_dpp v69, v67 row_bcast:31 row_mask:0xc bank_mask:0xf
	v_add_f32_e32 v67, v67, v69
	s_nop 0
	v_readlane_b32 s0, v67, 63
	v_mov_b32_e32 v67, v1
	s_nop 1
	v_mov_b32_dpp v67, v66 row_bcast:15 row_mask:0xa bank_mask:0xf
	v_add_f32_e32 v66, v66, v67
	v_mov_b32_e32 v67, v1
	s_nop 1
	v_mov_b32_dpp v67, v66 row_bcast:31 row_mask:0xc bank_mask:0xf
	v_add_f32_e32 v66, v66, v67
	s_nop 0
	v_readlane_b32 s1, v66, 63
	v_fma_f32 v66, s0, v220, v209
	s_mov_b32 s0, 0x800000
	v_cmp_gt_f32_e32 vcc, s0, v66
	v_mul_f32_e32 v67, 0x4b800000, v66
	s_nop 0
	v_cndmask_b32_e32 v66, v66, v67, vcc
	v_rsq_f32_e32 v66, v66
	s_nop 0
	v_mul_f32_e32 v67, 0x45800000, v66
	v_cndmask_b32_e32 v114, v66, v67, vcc
	v_fma_f32 v66, s1, v220, v209
	v_cmp_gt_f32_e32 vcc, s0, v66
	v_mul_f32_e32 v67, 0x4b800000, v66
	s_movk_i32 s0, 0xfff
	v_cndmask_b32_e32 v66, v66, v67, vcc
	v_rsq_f32_e32 v66, v66
	v_pk_mul_f32 v[30:31], v[30:31], v[114:115] op_sel_hi:[1,0]
	v_pk_mul_f32 v[32:33], v[32:33], v[114:115] op_sel_hi:[1,0]
	v_pk_mul_f32 v[26:27], v[26:27], v[114:115] op_sel_hi:[1,0]
	v_mul_f32_e32 v67, 0x45800000, v66
	v_cndmask_b32_e32 v116, v66, v67, vcc
	v_lshrrev_b32_e32 v66, 11, v68
	v_add_u32_e32 v66, 1, v66
	v_cmp_lt_i32_e32 vcc, s0, v102
	v_pk_mul_f32 v[62:63], v[62:63], v[116:117] op_sel_hi:[1,0]
	v_pk_mul_f32 v[28:29], v[28:29], v[114:115] op_sel_hi:[1,0]
	v_cndmask_b32_e32 v66, 0, v66, vcc
	v_add_u32_e32 v68, s6, v66
	v_mov_b64_e32 v[66:67], s[86:87]
	v_mad_u64_u32 v[66:67], s[0:1], v68, s65, v[66:67]
	s_mov_b64 s[0:1], 0x6000
	s_nop 0
	v_lshl_add_u64 v[118:119], v[66:67], 0, s[0:1]
	s_mov_b64 s[0:1], 0x8000
	v_lshl_add_u64 v[120:121], v[66:67], 0, s[0:1]
	v_lshl_add_u64 v[78:79], v[120:121], 0, v[0:1]
	v_lshl_add_u64 v[86:87], v[118:119], 0, v[0:1]
	global_load_dwordx4 v[66:69], v[96:97], off offset:16
	global_load_dwordx4 v[74:77], v[96:97], off
	global_load_dwordx4 v[70:73], v[78:79], off offset:16
	global_load_dwordx4 v[82:85], v[78:79], off
	s_nop 0
	global_load_dwordx4 v[78:81], v[86:87], off offset:16
	s_nop 0
	global_load_dwordx4 v[86:89], v[86:87], off
	global_load_dwordx4 v[132:135], v[96:97], off offset:2064
	global_load_dwordx4 v[136:139], v[96:97], off offset:2048
	v_lshl_add_u64 v[204:205], v[120:121], 0, v[104:105]
	global_load_dwordx4 v[140:143], v[204:205], off offset:16
	v_lshl_add_u64 v[204:205], v[120:121], 0, v[104:105]
	global_load_dwordx4 v[144:147], v[204:205], off
	v_lshl_add_u64 v[204:205], v[118:119], 0, v[104:105]
	global_load_dwordx4 v[148:151], v[204:205], off offset:16
	v_lshl_add_u64 v[204:205], v[118:119], 0, v[104:105]
	global_load_dwordx4 v[152:155], v[204:205], off
	global_load_dwordx4 v[156:159], v[98:99], off offset:16
	global_load_dwordx4 v[160:163], v[98:99], off
	v_lshl_add_u64 v[204:205], v[120:121], 0, v[106:107]
	global_load_dwordx4 v[164:167], v[204:205], off offset:16
	v_lshl_add_u64 v[204:205], v[120:121], 0, v[106:107]
	global_load_dwordx4 v[168:171], v[204:205], off
	v_lshl_add_u64 v[204:205], v[118:119], 0, v[106:107]
	global_load_dwordx4 v[172:175], v[204:205], off offset:16
	v_lshl_add_u64 v[204:205], v[118:119], 0, v[106:107]
	global_load_dwordx4 v[176:179], v[204:205], off
	global_load_dwordx4 v[180:183], v[94:95], off offset:16
	global_load_dwordx4 v[184:187], v[94:95], off
	v_lshl_add_u64 v[204:205], v[120:121], 0, v[108:109]
	global_load_dwordx4 v[188:191], v[204:205], off offset:16
	v_lshl_add_u64 v[204:205], v[120:121], 0, v[108:109]
	global_load_dwordx4 v[192:195], v[204:205], off
	v_lshl_add_u64 v[204:205], v[118:119], 0, v[108:109]
	global_load_dwordx4 v[196:199], v[204:205], off offset:16
	v_lshl_add_u64 v[204:205], v[118:119], 0, v[108:109]
	global_load_dwordx4 v[200:203], v[204:205], off
	v_pk_mul_f32 v[22:23], v[22:23], v[114:115] op_sel_hi:[1,0]
	v_pk_mul_f32 v[54:55], v[54:55], v[116:117] op_sel_hi:[1,0]
	v_pk_mul_f32 v[24:25], v[24:25], v[114:115] op_sel_hi:[1,0]
	v_pk_mul_f32 v[18:19], v[18:19], v[114:115] op_sel_hi:[1,0]
	v_pk_mul_f32 v[20:21], v[20:21], v[114:115] op_sel_hi:[1,0]
	v_pk_mul_f32 v[14:15], v[14:15], v[114:115] op_sel_hi:[1,0]
	v_pk_mul_f32 v[46:47], v[46:47], v[116:117] op_sel_hi:[1,0]
	v_pk_mul_f32 v[16:17], v[16:17], v[114:115] op_sel_hi:[1,0]
	v_pk_mul_f32 v[10:11], v[10:11], v[114:115] op_sel_hi:[1,0]
	v_pk_mul_f32 v[12:13], v[12:13], v[114:115] op_sel_hi:[1,0]
	v_pk_mul_f32 v[6:7], v[6:7], v[114:115] op_sel_hi:[1,0]
	v_pk_mul_f32 v[8:9], v[8:9], v[114:115] op_sel_hi:[1,0]
	v_pk_mul_f32 v[2:3], v[2:3], v[114:115] op_sel_hi:[1,0]
	v_pk_mul_f32 v[4:5], v[4:5], v[114:115] op_sel_hi:[1,0]
	v_readlane_b32 s0, v254, 39
	s_waitcnt vmcnt(18)
	v_pk_add_f32 v[82:83], v[82:83], 1.0 op_sel_hi:[1,0]
	s_nop 0
	v_pk_mul_f32 v[74:75], v[74:75], v[82:83]
	v_add_u32_e32 v102, s0, v102
	s_waitcnt vmcnt(18)
	v_pk_fma_f32 v[30:31], v[30:31], v[74:75], v[86:87]
	v_pk_fma_f32 v[62:63], v[62:63], v[74:75], v[86:87]
	v_pk_add_f32 v[74:75], v[84:85], 1.0 op_sel_hi:[1,0]
	v_cvt_pk_bf16_f32 v30, v30, v31
	v_pk_mul_f32 v[74:75], v[76:77], v[74:75]
	v_cvt_pk_bf16_f32 v62, v62, v63
	v_pk_fma_f32 v[32:33], v[32:33], v[74:75], v[88:89]
	s_nop 0
	v_cvt_pk_bf16_f32 v31, v32, v33
	v_pk_mul_f32 v[32:33], v[64:65], v[116:117] op_sel_hi:[1,0]
	s_nop 0
	v_pk_fma_f32 v[32:33], v[32:33], v[74:75], v[88:89]
	v_lshl_add_u64 v[74:75], v[118:119], 0, v[104:105]
	v_cvt_pk_bf16_f32 v63, v32, v33
	v_pk_add_f32 v[32:33], v[70:71], 1.0 op_sel_hi:[1,0]
	s_nop 0
	v_pk_mul_f32 v[64:65], v[66:67], v[32:33]
	v_lshl_add_u64 v[66:67], v[120:121], 0, v[104:105]
	v_pk_fma_f32 v[26:27], v[26:27], v[64:65], v[78:79]
	s_nop 0
	v_cvt_pk_bf16_f32 v32, v26, v27
	v_pk_mul_f32 v[26:27], v[58:59], v[116:117] op_sel_hi:[1,0]
	s_nop 0
	v_pk_fma_f32 v[26:27], v[26:27], v[64:65], v[78:79]
	s_nop 0
	v_cvt_pk_bf16_f32 v64, v26, v27
	v_pk_add_f32 v[26:27], v[72:73], 1.0 op_sel_hi:[1,0]
	s_nop 0
	v_pk_mul_f32 v[26:27], v[68:69], v[26:27]
	s_nop 0
	v_pk_fma_f32 v[28:29], v[28:29], v[26:27], v[80:81]
	s_nop 0
	v_cvt_pk_bf16_f32 v33, v28, v29
	v_pk_mul_f32 v[28:29], v[60:61], v[116:117] op_sel_hi:[1,0]
	s_nop 0
	v_pk_fma_f32 v[26:27], v[28:29], v[26:27], v[80:81]
	v_lshl_add_u64 v[28:29], v[100:101], 0, v[112:113]
	v_cvt_pk_bf16_f32 v65, v26, v27
	v_lshl_add_u64 v[26:27], v[100:101], 0, v[110:111]
	global_store_dwordx4 v[26:27], v[30:33], off
	global_store_dwordx4 v[28:29], v[62:65], off
	s_nop 0
	s_nop 0
	s_nop 0
	s_nop 0
	s_waitcnt vmcnt(12)
	v_pk_add_f32 v[66:67], v[144:145], 1.0 op_sel_hi:[1,0]
	s_nop 0
	v_pk_mul_f32 v[58:59], v[136:137], v[66:67]
	s_waitcnt vmcnt(12)
	v_pk_fma_f32 v[22:23], v[22:23], v[58:59], v[152:153]
	v_pk_fma_f32 v[54:55], v[54:55], v[58:59], v[152:153]
	v_pk_add_f32 v[58:59], v[146:147], 1.0 op_sel_hi:[1,0]
	v_cvt_pk_bf16_f32 v22, v22, v23
	v_pk_mul_f32 v[58:59], v[138:139], v[58:59]
	v_cvt_pk_bf16_f32 v54, v54, v55
	v_pk_fma_f32 v[24:25], v[24:25], v[58:59], v[154:155]
	s_nop 0
	v_cvt_pk_bf16_f32 v23, v24, v25
	v_pk_mul_f32 v[24:25], v[56:57], v[116:117] op_sel_hi:[1,0]
	s_nop 0
	v_pk_fma_f32 v[24:25], v[24:25], v[58:59], v[154:155]
	v_lshl_add_u64 v[58:59], v[118:119], 0, v[106:107]
	v_cvt_pk_bf16_f32 v55, v24, v25
	v_pk_add_f32 v[24:25], v[140:141], 1.0 op_sel_hi:[1,0]
	s_nop 0
	v_pk_mul_f32 v[30:31], v[132:133], v[24:25]
	s_nop 0
	v_pk_fma_f32 v[18:19], v[18:19], v[30:31], v[148:149]
	s_nop 0
	v_cvt_pk_bf16_f32 v24, v18, v19
	v_pk_mul_f32 v[18:19], v[50:51], v[116:117] op_sel_hi:[1,0]
	v_lshl_add_u64 v[50:51], v[120:121], 0, v[106:107]
	v_pk_fma_f32 v[18:19], v[18:19], v[30:31], v[148:149]
	s_nop 0
	v_cvt_pk_bf16_f32 v56, v18, v19
	v_pk_add_f32 v[18:19], v[142:143], 1.0 op_sel_hi:[1,0]
	s_nop 0
	v_pk_mul_f32 v[18:19], v[134:135], v[18:19]
	s_nop 0
	v_pk_fma_f32 v[20:21], v[20:21], v[18:19], v[150:151]
	s_nop 0
	v_cvt_pk_bf16_f32 v25, v20, v21
	v_pk_mul_f32 v[20:21], v[52:53], v[116:117] op_sel_hi:[1,0]
	s_nop 0
	v_pk_fma_f32 v[18:19], v[20:21], v[18:19], v[150:151]
	s_nop 0
	v_cvt_pk_bf16_f32 v57, v18, v19
	global_store_dwordx4 v[26:27], v[22:25], off offset:1024
	global_store_dwordx4 v[28:29], v[54:57], off offset:1024
	s_nop 0
	s_nop 0
	s_nop 0
	s_nop 0
	s_waitcnt vmcnt(6)
	v_pk_add_f32 v[50:51], v[168:169], 1.0 op_sel_hi:[1,0]
	s_nop 0
	v_pk_mul_f32 v[22:23], v[160:161], v[50:51]
	s_waitcnt vmcnt(6)
	v_pk_fma_f32 v[14:15], v[14:15], v[22:23], v[176:177]
	v_pk_fma_f32 v[22:23], v[46:47], v[22:23], v[176:177]
	v_pk_add_f32 v[46:47], v[170:171], 1.0 op_sel_hi:[1,0]
	v_cvt_pk_bf16_f32 v14, v14, v15
	v_pk_mul_f32 v[24:25], v[162:163], v[46:47]
	v_cvt_pk_bf16_f32 v22, v22, v23
	v_pk_fma_f32 v[16:17], v[16:17], v[24:25], v[178:179]
	s_nop 0
	v_cvt_pk_bf16_f32 v15, v16, v17
	v_pk_mul_f32 v[16:17], v[48:49], v[116:117] op_sel_hi:[1,0]
	s_nop 0
	v_pk_fma_f32 v[16:17], v[16:17], v[24:25], v[178:179]
	s_nop 0
	v_cvt_pk_bf16_f32 v23, v16, v17
	v_pk_add_f32 v[16:17], v[164:165], 1.0 op_sel_hi:[1,0]
	s_nop 0
	v_pk_mul_f32 v[18:19], v[156:157], v[16:17]
	s_nop 0
	v_pk_fma_f32 v[10:11], v[10:11], v[18:19], v[172:173]
	s_nop 0
	v_cvt_pk_bf16_f32 v16, v10, v11
	v_pk_mul_f32 v[10:11], v[42:43], v[116:117] op_sel_hi:[1,0]
	v_lshl_add_u64 v[42:43], v[118:119], 0, v[108:109]
	v_pk_fma_f32 v[10:11], v[10:11], v[18:19], v[172:173]
	s_nop 0
	v_cvt_pk_bf16_f32 v24, v10, v11
	v_pk_add_f32 v[10:11], v[166:167], 1.0 op_sel_hi:[1,0]
	s_nop 0
	v_pk_mul_f32 v[10:11], v[158:159], v[10:11]
	s_nop 0
	v_pk_fma_f32 v[12:13], v[12:13], v[10:11], v[174:175]
	s_nop 0
	v_cvt_pk_bf16_f32 v17, v12, v13
	v_pk_mul_f32 v[12:13], v[44:45], v[116:117] op_sel_hi:[1,0]
	s_nop 0
	v_pk_fma_f32 v[10:11], v[12:13], v[10:11], v[174:175]
	s_nop 0
	v_cvt_pk_bf16_f32 v25, v10, v11
	global_store_dwordx4 v[26:27], v[14:17], off offset:2048
	global_store_dwordx4 v[28:29], v[22:25], off offset:2048
	s_nop 1
	v_lshl_add_u64 v[22:23], v[120:121], 0, v[108:109]
	s_nop 0
	s_nop 0
	s_nop 0
	s_waitcnt vmcnt(0)
	v_pk_add_f32 v[22:23], v[192:193], 1.0 op_sel_hi:[1,0]
	s_nop 0
	v_pk_mul_f32 v[14:15], v[184:185], v[22:23]
	v_pk_mul_f32 v[22:23], v[38:39], v[116:117] op_sel_hi:[1,0]
	s_waitcnt vmcnt(0)
	v_pk_fma_f32 v[6:7], v[6:7], v[14:15], v[200:201]
	v_pk_fma_f32 v[14:15], v[22:23], v[14:15], v[200:201]
	v_pk_add_f32 v[22:23], v[194:195], 1.0 op_sel_hi:[1,0]
	v_cvt_pk_bf16_f32 v6, v6, v7
	v_pk_mul_f32 v[16:17], v[186:187], v[22:23]
	v_cvt_pk_bf16_f32 v14, v14, v15
	v_pk_fma_f32 v[8:9], v[8:9], v[16:17], v[202:203]
	s_nop 0
	v_cvt_pk_bf16_f32 v7, v8, v9
	v_pk_mul_f32 v[8:9], v[40:41], v[116:117] op_sel_hi:[1,0]
	s_nop 0
	v_pk_fma_f32 v[8:9], v[8:9], v[16:17], v[202:203]
	s_nop 0
	v_cvt_pk_bf16_f32 v15, v8, v9
	v_pk_add_f32 v[8:9], v[188:189], 1.0 op_sel_hi:[1,0]
	s_nop 0
	v_pk_mul_f32 v[10:11], v[180:181], v[8:9]
	s_nop 0
	v_pk_fma_f32 v[2:3], v[2:3], v[10:11], v[196:197]
	s_nop 0
	v_cvt_pk_bf16_f32 v8, v2, v3
	v_pk_mul_f32 v[2:3], v[34:35], v[116:117] op_sel_hi:[1,0]
	s_nop 0
	v_pk_fma_f32 v[2:3], v[2:3], v[10:11], v[196:197]
	s_nop 0
	v_cvt_pk_bf16_f32 v16, v2, v3
	v_pk_add_f32 v[2:3], v[190:191], 1.0 op_sel_hi:[1,0]
	s_nop 0
	v_pk_mul_f32 v[2:3], v[182:183], v[2:3]
	s_nop 0
	v_pk_fma_f32 v[4:5], v[4:5], v[2:3], v[198:199]
	s_nop 0
	v_cvt_pk_bf16_f32 v9, v4, v5
	v_pk_mul_f32 v[4:5], v[36:37], v[116:117] op_sel_hi:[1,0]
	s_nop 0
	v_pk_fma_f32 v[2:3], v[4:5], v[2:3], v[198:199]
	s_nop 0
	v_cvt_pk_bf16_f32 v17, v2, v3
	global_store_dwordx4 v[26:27], v[6:9], off offset:3072
	global_store_dwordx4 v[28:29], v[14:17], off offset:3072
	s_cbranch_scc1 .LBB0_100

.LBB0_897:
	s_waitcnt vmcnt(0)
	v_pk_mul_f32 v[66:67], v[34:35], v[34:35]
	v_pk_mul_f32 v[76:77], v[26:27], v[26:27]
	v_mov_b32_e32 v124, v10
	v_mov_b32_e32 v125, v14
	v_pk_mul_f32 v[70:71], v[36:37], v[36:37]
	v_pk_mul_f32 v[78:79], v[28:29], v[28:29]
	v_pk_mul_f32 v[124:125], v[124:125], v[124:125]
	v_mov_b32_e32 v126, v11
	v_mov_b32_e32 v127, v15
	v_add_f32_e32 v66, v67, v66
	v_add_f32_e32 v67, v77, v76
	v_pk_fma_f32 v[124:125], v[126:127], v[126:127], v[124:125]
	v_mov_b32_e32 v126, v12
	v_mov_b32_e32 v127, v16
	v_add_f32_e32 v66, v70, v66
	v_add_f32_e32 v67, v78, v67
	v_pk_mul_f32 v[84:85], v[22:23], v[22:23]
	v_pk_fma_f32 v[124:125], v[126:127], v[126:127], v[124:125]
	v_mov_b32_e32 v126, v13
	v_mov_b32_e32 v127, v17
	v_add_f32_e32 v66, v71, v66
	v_add_f32_e32 v67, v79, v67
	v_pk_mul_f32 v[86:87], v[24:25], v[24:25]
	v_pk_fma_f32 v[124:125], v[126:127], v[126:127], v[124:125]
	v_mov_b32_e32 v126, v42
	v_mov_b32_e32 v127, v46
	v_add_f32_e32 v66, v67, v66
	v_add_f32_e32 v67, v85, v84
	v_pk_mul_f32 v[126:127], v[126:127], v[126:127]
	v_mov_b32_e32 v128, v43
	v_mov_b32_e32 v129, v47
	v_add_f32_e32 v67, v86, v67
	v_pk_mul_f32 v[116:117], v[18:19], v[18:19]
	v_pk_fma_f32 v[126:127], v[128:129], v[128:129], v[126:127]
	v_mov_b32_e32 v128, v44
	v_mov_b32_e32 v129, v48
	v_add_f32_e32 v67, v87, v67
	v_pk_mul_f32 v[118:119], v[20:21], v[20:21]
	v_pk_fma_f32 v[126:127], v[128:129], v[128:129], v[126:127]
	v_mov_b32_e32 v128, v45
	v_mov_b32_e32 v129, v49
	v_add_f32_e32 v66, v67, v66
	v_add_f32_e32 v67, v117, v116
	v_pk_fma_f32 v[126:127], v[128:129], v[128:129], v[126:127]
	v_mov_b32_e32 v128, v2
	v_mov_b32_e32 v129, v6
	v_add_f32_e32 v67, v118, v67
	v_pk_mul_f32 v[128:129], v[128:129], v[128:129]
	v_mov_b32_e32 v130, v3
	v_mov_b32_e32 v131, v7
	v_add_f32_e32 v67, v119, v67
	v_pk_fma_f32 v[128:129], v[130:131], v[130:131], v[128:129]
	v_mov_b32_e32 v130, v4
	v_mov_b32_e32 v131, v8
	v_add_f32_e32 v66, v67, v66
	v_pk_fma_f32 v[128:129], v[130:131], v[130:131], v[128:129]
	v_mov_b32_e32 v130, v5
	v_mov_b32_e32 v131, v9
	v_add_f32_e32 v66, v125, v66
	v_pk_fma_f32 v[128:129], v[130:131], v[130:131], v[128:129]
	v_add_f32_e32 v66, v124, v66
	v_add_f32_e32 v66, v129, v66
	v_add_f32_e32 v69, v128, v66
	v_mov_b32_e32 v66, v30
	v_mov_b32_e32 v67, v38
	v_pk_mul_f32 v[66:67], v[66:67], v[66:67]
	v_mov_b32_e32 v70, v31
	v_mov_b32_e32 v71, v39
	v_pk_fma_f32 v[66:67], v[70:71], v[70:71], v[66:67]
	v_mov_b32_e32 v70, v32
	v_mov_b32_e32 v71, v40
	v_pk_mul_f32 v[72:73], v[62:63], v[62:63]
	v_pk_mul_f32 v[80:81], v[58:59], v[58:59]
	v_pk_fma_f32 v[66:67], v[70:71], v[70:71], v[66:67]
	v_mov_b32_e32 v70, v33
	v_mov_b32_e32 v71, v41
	v_pk_mul_f32 v[74:75], v[64:65], v[64:65]
	v_pk_mul_f32 v[82:83], v[60:61], v[60:61]
	v_pk_fma_f32 v[66:67], v[70:71], v[70:71], v[66:67]
	v_add_f32_e32 v70, v73, v72
	v_add_f32_e32 v71, v81, v80
	v_add_f32_e32 v70, v74, v70
	v_add_f32_e32 v71, v82, v71
	v_pk_mul_f32 v[88:89], v[54:55], v[54:55]
	v_add_f32_e32 v70, v75, v70
	v_add_f32_e32 v71, v83, v71
	v_pk_mul_f32 v[114:115], v[56:57], v[56:57]
	v_add_f32_e32 v70, v71, v70
	v_add_f32_e32 v71, v89, v88
	v_add_f32_e32 v71, v114, v71
	v_pk_mul_f32 v[120:121], v[50:51], v[50:51]
	v_add_f32_e32 v71, v115, v71
	v_pk_mul_f32 v[122:123], v[52:53], v[52:53]
	v_add_f32_e32 v70, v71, v70
	v_add_f32_e32 v71, v121, v120
	v_add_f32_e32 v71, v122, v71
	v_add_f32_e32 v71, v123, v71
	v_add_f32_e32 v70, v71, v70
	v_add_f32_e32 v70, v127, v70
	v_add_f32_e32 v70, v126, v70
	v_add_f32_e32 v67, v67, v70
	v_add_f32_e32 v66, v66, v67
	v_mov_b32_e32 v105, v1
	v_add_f32_dpp v67, v69, v69 quad_perm:[1,0,3,2] row_mask:0xf bank_mask:0xf bound_ctrl:1
	v_mov_b32_e32 v69, v1
	v_add_f32_dpp v66, v66, v66 quad_perm:[1,0,3,2] row_mask:0xf bank_mask:0xf bound_ctrl:1
	v_add_f32_dpp v67, v67, v67 quad_perm:[2,3,0,1] row_mask:0xf bank_mask:0xf bound_ctrl:1
	v_mov_b32_e32 v107, v1
	v_add_f32_dpp v66, v66, v66 quad_perm:[2,3,0,1] row_mask:0xf bank_mask:0xf bound_ctrl:1
	v_add_f32_dpp v67, v67, v67 row_half_mirror row_mask:0xf bank_mask:0xf bound_ctrl:1
	v_mov_b32_e32 v109, v1
	v_add_f32_dpp v66, v66, v66 row_half_mirror row_mask:0xf bank_mask:0xf bound_ctrl:1
	v_add_f32_dpp v67, v67, v67 row_mirror row_mask:0xf bank_mask:0xf bound_ctrl:1
	s_add_i32 s9, s9, s96
	v_add_f32_dpp v66, v66, v66 row_mirror row_mask:0xf bank_mask:0xf bound_ctrl:1
	v_mov_b32_dpp v69, v67 row_bcast:15 row_mask:0xa bank_mask:0xf
	v_add_f32_e32 v67, v67, v69
	v_mov_b32_e32 v69, v1
	s_cmpk_gt_i32 s9, 0x2ff
	s_nop 0
	v_mov_b32_dpp v69, v67 row_bcast:31 row_mask:0xc bank_mask:0xf
	v_add_f32_e32 v67, v67, v69
	s_nop 0
	v_readlane_b32 s0, v67, 63
	v_mov_b32_e32 v67, v1
	s_nop 1
	v_mov_b32_dpp v67, v66 row_bcast:15 row_mask:0xa bank_mask:0xf
	v_add_f32_e32 v66, v66, v67
	v_mov_b32_e32 v67, v1
	s_nop 1
	v_mov_b32_dpp v67, v66 row_bcast:31 row_mask:0xc bank_mask:0xf
	v_add_f32_e32 v66, v66, v67
	s_nop 0
	v_readlane_b32 s1, v66, 63
	v_fma_f32 v66, s0, v220, v209
	s_mov_b32 s0, 0x800000
	v_cmp_gt_f32_e32 vcc, s0, v66
	v_mul_f32_e32 v67, 0x4b800000, v66
	s_nop 0
	v_cndmask_b32_e32 v66, v66, v67, vcc
	v_rsq_f32_e32 v66, v66
	s_nop 0
	v_mul_f32_e32 v67, 0x45800000, v66
	v_cndmask_b32_e32 v114, v66, v67, vcc
	v_fma_f32 v66, s1, v220, v209
	v_cmp_gt_f32_e32 vcc, s0, v66
	v_mul_f32_e32 v67, 0x4b800000, v66
	s_movk_i32 s0, 0xfff
	v_cndmask_b32_e32 v66, v66, v67, vcc
	v_rsq_f32_e32 v66, v66
	v_pk_mul_f32 v[34:35], v[34:35], v[114:115] op_sel_hi:[1,0]
	v_pk_mul_f32 v[36:37], v[36:37], v[114:115] op_sel_hi:[1,0]
	v_pk_mul_f32 v[26:27], v[26:27], v[114:115] op_sel_hi:[1,0]
	v_mul_f32_e32 v67, 0x45800000, v66
	v_cndmask_b32_e32 v116, v66, v67, vcc
	v_lshrrev_b32_e32 v66, 11, v68
	v_add_u32_e32 v66, 1, v66
	v_cmp_lt_i32_e32 vcc, s0, v102
	v_pk_mul_f32 v[62:63], v[62:63], v[116:117] op_sel_hi:[1,0]
	v_pk_mul_f32 v[28:29], v[28:29], v[114:115] op_sel_hi:[1,0]
	v_cndmask_b32_e32 v66, 0, v66, vcc
	v_add_u32_e32 v68, s8, v66
	v_mov_b64_e32 v[66:67], s[86:87]
	v_mad_u64_u32 v[118:119], s[0:1], v68, s65, v[66:67]
	s_mov_b64 s[0:1], 0x2000
	s_nop 0
	v_lshl_add_u64 v[120:121], v[118:119], 0, s[0:1]
	v_lshl_add_u64 v[78:79], v[120:121], 0, v[0:1]
	v_lshl_add_u64 v[122:123], v[118:119], 0, v[0:1]
	global_load_dwordx4 v[66:69], v[96:97], off offset:16
	global_load_dwordx4 v[74:77], v[96:97], off
	global_load_dwordx4 v[70:73], v[78:79], off offset:16
	global_load_dwordx4 v[82:85], v[78:79], off
	s_nop 0
	global_load_dwordx4 v[78:81], v[122:123], off offset:16
	global_load_dwordx4 v[86:89], v[122:123], off
	global_load_dwordx4 v[132:135], v[96:97], off offset:2064
	global_load_dwordx4 v[136:139], v[96:97], off offset:2048
	v_lshl_add_u64 v[204:205], v[120:121], 0, v[104:105]
	global_load_dwordx4 v[140:143], v[204:205], off offset:16
	v_lshl_add_u64 v[204:205], v[120:121], 0, v[104:105]
	global_load_dwordx4 v[144:147], v[204:205], off
	global_load_dwordx4 v[148:151], v[122:123], off offset:2064
	global_load_dwordx4 v[152:155], v[122:123], off offset:2048
	global_load_dwordx4 v[156:159], v[98:99], off offset:16
	global_load_dwordx4 v[160:163], v[98:99], off
	v_lshl_add_u64 v[204:205], v[120:121], 0, v[106:107]
	global_load_dwordx4 v[164:167], v[204:205], off offset:16
	v_lshl_add_u64 v[204:205], v[120:121], 0, v[106:107]
	global_load_dwordx4 v[168:171], v[204:205], off
	v_lshl_add_u64 v[204:205], v[118:119], 0, v[106:107]
	global_load_dwordx4 v[172:175], v[204:205], off offset:16
	v_lshl_add_u64 v[204:205], v[118:119], 0, v[106:107]
	global_load_dwordx4 v[176:179], v[204:205], off
	global_load_dwordx4 v[180:183], v[94:95], off offset:16
	global_load_dwordx4 v[184:187], v[94:95], off
	v_lshl_add_u64 v[204:205], v[120:121], 0, v[108:109]
	global_load_dwordx4 v[188:191], v[204:205], off offset:16
	v_lshl_add_u64 v[204:205], v[120:121], 0, v[108:109]
	global_load_dwordx4 v[192:195], v[204:205], off
	v_lshl_add_u64 v[204:205], v[118:119], 0, v[108:109]
	global_load_dwordx4 v[196:199], v[204:205], off offset:16
	v_lshl_add_u64 v[204:205], v[118:119], 0, v[108:109]
	global_load_dwordx4 v[200:203], v[204:205], off
	v_pk_mul_f32 v[22:23], v[22:23], v[114:115] op_sel_hi:[1,0]
	v_pk_mul_f32 v[54:55], v[54:55], v[116:117] op_sel_hi:[1,0]
	v_pk_mul_f32 v[24:25], v[24:25], v[114:115] op_sel_hi:[1,0]
	v_pk_mul_f32 v[18:19], v[18:19], v[114:115] op_sel_hi:[1,0]
	v_pk_mul_f32 v[20:21], v[20:21], v[114:115] op_sel_hi:[1,0]
	v_pk_mul_f32 v[14:15], v[14:15], v[114:115] op_sel_hi:[1,0]
	v_pk_mul_f32 v[46:47], v[46:47], v[116:117] op_sel_hi:[1,0]
	v_pk_mul_f32 v[16:17], v[16:17], v[114:115] op_sel_hi:[1,0]
	v_pk_mul_f32 v[10:11], v[10:11], v[114:115] op_sel_hi:[1,0]
	v_pk_mul_f32 v[12:13], v[12:13], v[114:115] op_sel_hi:[1,0]
	v_pk_mul_f32 v[6:7], v[6:7], v[114:115] op_sel_hi:[1,0]
	v_pk_mul_f32 v[8:9], v[8:9], v[114:115] op_sel_hi:[1,0]
	v_pk_mul_f32 v[2:3], v[2:3], v[114:115] op_sel_hi:[1,0]
	v_pk_mul_f32 v[4:5], v[4:5], v[114:115] op_sel_hi:[1,0]
	v_readlane_b32 s0, v254, 39
	s_waitcnt vmcnt(18)
	v_pk_add_f32 v[82:83], v[82:83], 1.0 op_sel_hi:[1,0]
	s_nop 0
	v_pk_mul_f32 v[74:75], v[74:75], v[82:83]
	v_add_u32_e32 v102, s0, v102
	v_pk_fma_f32 v[34:35], v[34:35], v[74:75], v[86:87]
	v_pk_fma_f32 v[62:63], v[62:63], v[74:75], v[86:87]
	v_pk_add_f32 v[74:75], v[84:85], 1.0 op_sel_hi:[1,0]
	v_cvt_pk_bf16_f32 v34, v34, v35
	v_pk_mul_f32 v[74:75], v[76:77], v[74:75]
	v_cvt_pk_bf16_f32 v62, v62, v63
	v_pk_fma_f32 v[36:37], v[36:37], v[74:75], v[88:89]
	s_nop 0
	v_cvt_pk_bf16_f32 v35, v36, v37
	v_pk_mul_f32 v[36:37], v[64:65], v[116:117] op_sel_hi:[1,0]
	s_nop 0
	v_pk_fma_f32 v[36:37], v[36:37], v[74:75], v[88:89]
	s_nop 0
	v_cvt_pk_bf16_f32 v63, v36, v37
	v_pk_add_f32 v[36:37], v[70:71], 1.0 op_sel_hi:[1,0]
	s_nop 0
	v_pk_mul_f32 v[64:65], v[66:67], v[36:37]
	v_lshl_add_u64 v[66:67], v[120:121], 0, v[104:105]
	v_pk_fma_f32 v[26:27], v[26:27], v[64:65], v[78:79]
	s_nop 0
	v_cvt_pk_bf16_f32 v36, v26, v27
	v_pk_mul_f32 v[26:27], v[58:59], v[116:117] op_sel_hi:[1,0]
	s_nop 0
	v_pk_fma_f32 v[26:27], v[26:27], v[64:65], v[78:79]
	s_nop 0
	v_cvt_pk_bf16_f32 v64, v26, v27
	v_pk_add_f32 v[26:27], v[72:73], 1.0 op_sel_hi:[1,0]
	s_nop 0
	v_pk_mul_f32 v[26:27], v[68:69], v[26:27]
	s_nop 0
	v_pk_fma_f32 v[28:29], v[28:29], v[26:27], v[80:81]
	s_nop 0
	v_cvt_pk_bf16_f32 v37, v28, v29
	v_pk_mul_f32 v[28:29], v[60:61], v[116:117] op_sel_hi:[1,0]
	s_nop 0
	v_pk_fma_f32 v[26:27], v[28:29], v[26:27], v[80:81]
	v_lshl_add_u64 v[28:29], v[100:101], 0, v[112:113]
	v_cvt_pk_bf16_f32 v65, v26, v27
	v_lshl_add_u64 v[26:27], v[100:101], 0, v[110:111]
	global_store_dwordx4 v[26:27], v[34:37], off
	global_store_dwordx4 v[28:29], v[62:65], off
	s_nop 0
	s_nop 0
	s_nop 0
	s_waitcnt vmcnt(12)
	v_pk_add_f32 v[66:67], v[144:145], 1.0 op_sel_hi:[1,0]
	s_nop 0
	v_pk_mul_f32 v[58:59], v[136:137], v[66:67]
	s_nop 0
	v_pk_fma_f32 v[22:23], v[22:23], v[58:59], v[152:153]
	v_pk_fma_f32 v[54:55], v[54:55], v[58:59], v[152:153]
	v_pk_add_f32 v[58:59], v[146:147], 1.0 op_sel_hi:[1,0]
	v_cvt_pk_bf16_f32 v22, v22, v23
	v_pk_mul_f32 v[58:59], v[138:139], v[58:59]
	v_cvt_pk_bf16_f32 v54, v54, v55
	v_pk_fma_f32 v[24:25], v[24:25], v[58:59], v[154:155]
	s_nop 0
	v_cvt_pk_bf16_f32 v23, v24, v25
	v_pk_mul_f32 v[24:25], v[56:57], v[116:117] op_sel_hi:[1,0]
	s_nop 0
	v_pk_fma_f32 v[24:25], v[24:25], v[58:59], v[154:155]
	v_lshl_add_u64 v[58:59], v[118:119], 0, v[106:107]
	v_cvt_pk_bf16_f32 v55, v24, v25
	v_pk_add_f32 v[24:25], v[140:141], 1.0 op_sel_hi:[1,0]
	s_nop 0
	v_pk_mul_f32 v[34:35], v[132:133], v[24:25]
	s_nop 0
	v_pk_fma_f32 v[18:19], v[18:19], v[34:35], v[148:149]
	s_nop 0
	v_cvt_pk_bf16_f32 v24, v18, v19
	v_pk_mul_f32 v[18:19], v[50:51], v[116:117] op_sel_hi:[1,0]
	v_lshl_add_u64 v[50:51], v[120:121], 0, v[106:107]
	v_pk_fma_f32 v[18:19], v[18:19], v[34:35], v[148:149]
	s_nop 0
	v_cvt_pk_bf16_f32 v56, v18, v19
	v_pk_add_f32 v[18:19], v[142:143], 1.0 op_sel_hi:[1,0]
	s_nop 0
	v_pk_mul_f32 v[18:19], v[134:135], v[18:19]
	s_nop 0
	v_pk_fma_f32 v[20:21], v[20:21], v[18:19], v[150:151]
	s_nop 0
	v_cvt_pk_bf16_f32 v25, v20, v21
	v_pk_mul_f32 v[20:21], v[52:53], v[116:117] op_sel_hi:[1,0]
	s_nop 0
	v_pk_fma_f32 v[18:19], v[20:21], v[18:19], v[150:151]
	s_nop 0
	v_cvt_pk_bf16_f32 v57, v18, v19
	global_store_dwordx4 v[26:27], v[22:25], off offset:1024
	global_store_dwordx4 v[28:29], v[54:57], off offset:1024
	s_nop 0
	s_nop 0
	s_nop 0
	s_nop 0
	s_waitcnt vmcnt(6)
	v_pk_add_f32 v[50:51], v[168:169], 1.0 op_sel_hi:[1,0]
	s_nop 0
	v_pk_mul_f32 v[22:23], v[160:161], v[50:51]
	s_nop 0
	v_pk_fma_f32 v[14:15], v[14:15], v[22:23], v[176:177]
	v_pk_fma_f32 v[22:23], v[46:47], v[22:23], v[176:177]
	v_pk_add_f32 v[46:47], v[170:171], 1.0 op_sel_hi:[1,0]
	v_cvt_pk_bf16_f32 v14, v14, v15
	v_pk_mul_f32 v[24:25], v[162:163], v[46:47]
	v_cvt_pk_bf16_f32 v22, v22, v23
	v_pk_fma_f32 v[16:17], v[16:17], v[24:25], v[178:179]
	s_nop 0
	v_cvt_pk_bf16_f32 v15, v16, v17
	v_pk_mul_f32 v[16:17], v[48:49], v[116:117] op_sel_hi:[1,0]
	s_nop 0
	v_pk_fma_f32 v[16:17], v[16:17], v[24:25], v[178:179]
	s_nop 0
	v_cvt_pk_bf16_f32 v23, v16, v17
	v_pk_add_f32 v[16:17], v[164:165], 1.0 op_sel_hi:[1,0]
	s_nop 0
	v_pk_mul_f32 v[18:19], v[156:157], v[16:17]
	s_nop 0
	v_pk_fma_f32 v[10:11], v[10:11], v[18:19], v[172:173]
	s_nop 0
	v_cvt_pk_bf16_f32 v16, v10, v11
	v_pk_mul_f32 v[10:11], v[42:43], v[116:117] op_sel_hi:[1,0]
	v_lshl_add_u64 v[42:43], v[118:119], 0, v[108:109]
	v_pk_fma_f32 v[10:11], v[10:11], v[18:19], v[172:173]
	s_nop 0
	v_cvt_pk_bf16_f32 v24, v10, v11
	v_pk_add_f32 v[10:11], v[166:167], 1.0 op_sel_hi:[1,0]
	s_nop 0
	v_pk_mul_f32 v[10:11], v[158:159], v[10:11]
	s_nop 0
	v_pk_fma_f32 v[12:13], v[12:13], v[10:11], v[174:175]
	s_nop 0
	v_cvt_pk_bf16_f32 v17, v12, v13
	v_pk_mul_f32 v[12:13], v[44:45], v[116:117] op_sel_hi:[1,0]
	s_nop 0
	v_pk_fma_f32 v[10:11], v[12:13], v[10:11], v[174:175]
	s_nop 0
	v_cvt_pk_bf16_f32 v25, v10, v11
	global_store_dwordx4 v[26:27], v[14:17], off offset:2048
	global_store_dwordx4 v[28:29], v[22:25], off offset:2048
	s_nop 1
	v_lshl_add_u64 v[22:23], v[120:121], 0, v[108:109]
	s_nop 0
	s_nop 0
	s_nop 0
	s_waitcnt vmcnt(0)
	v_pk_add_f32 v[22:23], v[192:193], 1.0 op_sel_hi:[1,0]
	s_nop 0
	v_pk_mul_f32 v[14:15], v[184:185], v[22:23]
	v_pk_mul_f32 v[22:23], v[38:39], v[116:117] op_sel_hi:[1,0]
	v_pk_fma_f32 v[6:7], v[6:7], v[14:15], v[200:201]
	v_pk_fma_f32 v[14:15], v[22:23], v[14:15], v[200:201]
	v_pk_add_f32 v[22:23], v[194:195], 1.0 op_sel_hi:[1,0]
	v_cvt_pk_bf16_f32 v6, v6, v7
	v_pk_mul_f32 v[16:17], v[186:187], v[22:23]
	v_cvt_pk_bf16_f32 v14, v14, v15
	v_pk_fma_f32 v[8:9], v[8:9], v[16:17], v[202:203]
	s_nop 0
	v_cvt_pk_bf16_f32 v7, v8, v9
	v_pk_mul_f32 v[8:9], v[40:41], v[116:117] op_sel_hi:[1,0]
	s_nop 0
	v_pk_fma_f32 v[8:9], v[8:9], v[16:17], v[202:203]
	s_nop 0
	v_cvt_pk_bf16_f32 v15, v8, v9
	v_pk_add_f32 v[8:9], v[188:189], 1.0 op_sel_hi:[1,0]
	s_nop 0
	v_pk_mul_f32 v[10:11], v[180:181], v[8:9]
	s_nop 0
	v_pk_fma_f32 v[2:3], v[2:3], v[10:11], v[196:197]
	s_nop 0
	v_cvt_pk_bf16_f32 v8, v2, v3
	v_pk_mul_f32 v[2:3], v[30:31], v[116:117] op_sel_hi:[1,0]
	s_nop 0
	v_pk_fma_f32 v[2:3], v[2:3], v[10:11], v[196:197]
	s_nop 0
	v_cvt_pk_bf16_f32 v16, v2, v3
	v_pk_add_f32 v[2:3], v[190:191], 1.0 op_sel_hi:[1,0]
	s_nop 0
	v_pk_mul_f32 v[2:3], v[182:183], v[2:3]
	s_nop 0
	v_pk_fma_f32 v[4:5], v[4:5], v[2:3], v[198:199]
	s_nop 0
	v_cvt_pk_bf16_f32 v9, v4, v5
	v_pk_mul_f32 v[4:5], v[32:33], v[116:117] op_sel_hi:[1,0]
	s_nop 0
	v_pk_fma_f32 v[2:3], v[4:5], v[2:3], v[198:199]
	s_nop 0
	v_cvt_pk_bf16_f32 v17, v2, v3
	global_store_dwordx4 v[26:27], v[6:9], off offset:3072
	global_store_dwordx4 v[28:29], v[14:17], off offset:3072
	s_cbranch_scc1 .LBB0_905
